# v12: v8 + attention QK^T K-fragment LDS reads pipelined through 6 rotating register buffers (counted lgkmcnt), same MFMA order; bit-exact
# baseline (speedup 1.0000x reference)
; #define LAS __attribute__((address_space(3)))
; __device__ __forceinline__ void attn_phase(LAS unsigned char* lds, const bf16_t* Q, const bf16_t* KN, const bf16_t* P, const bf16_t* VT, bf16_t* CAT, int bid, int G, const int tid) {
;     ...
;             LAS unsigned char* buf = lds + (kt & 1) * BUFB;
;             *(LAS u32x4*)(buf + lk) = rk0; *(LAS u32x4*)(buf + lk + 32 * KS * 2) = rk1; *(LAS u32x4*)(buf + lp) = rp;
;             *(LAS u32x4*)(buf + lv) = rv0; *(LAS u32x4*)(buf + lv + 64 * VS * 2) = rv1;
;             __syncthreads();
;             if (kt + 1 < nt) {
;                 const size_t ko = (size_t)(kt + 1) * 64;
;                 rk0 = *(const u32x4*)(gk + ko * 1024); rk1 = *(const u32x4*)(gk + (ko + 32) * 1024); rp = *(const u32x4*)(gp + ko * P_LD);
;                 rv0 = *(const u32x4*)(gv + ko); rv1 = *(const u32x4*)(gv + (size_t)64 * M + ko);
;             }
;             if (kt * 64 <= qlo + 31) {
;                 f32x4 s[4][2];
; #pragma unroll
;                 for (int kb = 0; kb < 4; ++kb) { s[kb][0] = (f32x4){0.f, 0.f, 0.f, 0.f}; s[kb][1] = (f32x4){0.f, 0.f, 0.f, 0.f}; }
; #pragma unroll
;                 for (int ch = 0; ch < 6; ++ch) {
; #pragma unroll
;                     for (int kb = 0; kb < 4; ++kb) {
;                         const bf16x8 kf = *(const LAS bf16x8*)(buf + ((kb * 16 + fr) * KS + ch * 32 + fq * 8) * 2);
;                         s[kb][0] = __builtin_amdgcn_mfma_f32_16x16x32_bf16(kf, qf[0][ch], s[kb][0], 0, 0, 0);
;                         s[kb][1] = __builtin_amdgcn_mfma_f32_16x16x32_bf16(kf, qf[1][ch], s[kb][1], 0, 0, 0);
;                     }
;                     if (ch & 1) asm volatile("" ::: "memory");
;                 }
.LBB0_146:
	s_bitcmp1_b32 s34, 0
	s_cselect_b32 s4, 0xac00, 0
	s_add_i32 s35, s4, 0
	v_add_u32_e32 v132, s35, v183
	s_waitcnt vmcnt(0) lgkmcnt(0)
	ds_write_b128 v132, v[112:115]
	ds_write_b128 v132, v[116:119] offset:12800
	v_add_u32_e32 v112, s35, v240
	ds_write_b128 v112, v[120:123]
	v_add_u32_e32 v112, s35, v241
	ds_write_b128 v112, v[124:127] offset:25600
	ds_write_b128 v112, v[128:131] offset:34816
	v_lshl_add_u64 v[112:113], s[24:25], 0, v[166:167]
	s_mov_b32 s4, 0x1c220000
	v_add_co_u32_e32 v114, vcc, s4, v112
	s_mov_b32 s4, 0x1c230000
	s_nop 0
	v_addc_co_u32_e32 v115, vcc, 0, v113, vcc
	v_add_co_u32_e32 v116, vcc, s4, v112
	v_lshl_add_u64 v[128:129], s[24:25], 0, v[168:169]
	s_nop 0
	v_addc_co_u32_e32 v117, vcc, 0, v113, vcc
	v_add_co_u32_e32 v124, vcc, 0x20200000, v128
	v_lshl_add_u64 v[120:121], s[24:25], 0, v[164:165]
	s_nop 0
	v_addc_co_u32_e32 v125, vcc, 0, v129, vcc
	v_add_co_u32_e32 v128, vcc, 0x20600000, v128
	s_waitcnt lgkmcnt(0)
	s_nop 0
	v_addc_co_u32_e32 v129, vcc, 0, v129, vcc
	s_barrier
	flat_load_dwordx4 v[112:115], v[114:115]
	s_nop 0
	flat_load_dwordx4 v[116:119], v[116:117]
	s_nop 0
	flat_load_dwordx4 v[120:123], v[120:121]
	s_nop 0
	flat_load_dwordx4 v[124:127], v[124:125] offset:128
	s_cmp_gt_i32 s30, s26
	flat_load_dwordx4 v[128:131], v[128:129] offset:128
	s_cbranch_scc1 .LBB0_145
	v_add3_u32 v174, s35, v182, v181
	ds_read_b128 v[170:173], v174
	ds_read_b128 v[208:211], v174 offset:6400
	ds_read_b128 v[212:215], v174 offset:12800
	ds_read_b128 v[216:219], v174 offset:19200
	ds_read_b128 v[220:223], v174 offset:64
	ds_read_b128 v[224:227], v174 offset:6464
	s_add_i32 s4, s30, 63
	s_cmp_le_i32 s4, s21
	s_waitcnt lgkmcnt(5)
	v_mfma_f32_16x16x32_bf16 v[132:135], v[170:173], v[104:107], 0
	v_mfma_f32_16x16x32_bf16 v[148:151], v[170:173], v[108:111], 0
	ds_read_b128 v[170:173], v174 offset:12864
	s_waitcnt lgkmcnt(5)
	v_mfma_f32_16x16x32_bf16 v[136:139], v[208:211], v[104:107], 0
	v_mfma_f32_16x16x32_bf16 v[156:159], v[208:211], v[108:111], 0
	ds_read_b128 v[208:211], v174 offset:19264
	s_waitcnt lgkmcnt(5)
	v_mfma_f32_16x16x32_bf16 v[140:143], v[212:215], v[104:107], 0
	v_mfma_f32_16x16x32_bf16 v[152:155], v[212:215], v[108:111], 0
	ds_read_b128 v[212:215], v174 offset:128
	s_waitcnt lgkmcnt(5)
	v_mfma_f32_16x16x32_bf16 v[144:147], v[216:219], v[104:107], 0
	v_mfma_f32_16x16x32_bf16 v[160:163], v[216:219], v[108:111], 0
	ds_read_b128 v[216:219], v174 offset:6528
	s_waitcnt lgkmcnt(5)
	v_mfma_f32_16x16x32_bf16 v[132:135], v[220:223], v[92:95], v[132:135]
	v_mfma_f32_16x16x32_bf16 v[148:151], v[220:223], v[100:103], v[148:151]
	ds_read_b128 v[220:223], v174 offset:12928
	s_waitcnt lgkmcnt(5)
	v_mfma_f32_16x16x32_bf16 v[136:139], v[224:227], v[92:95], v[136:139]
	v_mfma_f32_16x16x32_bf16 v[156:159], v[224:227], v[100:103], v[156:159]
	ds_read_b128 v[224:227], v174 offset:19328
	s_waitcnt lgkmcnt(5)
	v_mfma_f32_16x16x32_bf16 v[140:143], v[170:173], v[92:95], v[140:143]
	v_mfma_f32_16x16x32_bf16 v[152:155], v[170:173], v[100:103], v[152:155]
	ds_read_b128 v[170:173], v174 offset:192
	s_waitcnt lgkmcnt(5)
	v_mfma_f32_16x16x32_bf16 v[144:147], v[208:211], v[92:95], v[144:147]
	v_mfma_f32_16x16x32_bf16 v[160:163], v[208:211], v[100:103], v[160:163]
	ds_read_b128 v[208:211], v174 offset:6592
	s_waitcnt lgkmcnt(5)
	v_mfma_f32_16x16x32_bf16 v[132:135], v[212:215], v[88:91], v[132:135]
	v_mfma_f32_16x16x32_bf16 v[148:151], v[212:215], v[96:99], v[148:151]
	ds_read_b128 v[212:215], v174 offset:12992
	s_waitcnt lgkmcnt(5)
	v_mfma_f32_16x16x32_bf16 v[136:139], v[216:219], v[88:91], v[136:139]
	v_mfma_f32_16x16x32_bf16 v[156:159], v[216:219], v[96:99], v[156:159]
	ds_read_b128 v[216:219], v174 offset:19392
	s_waitcnt lgkmcnt(5)
	v_mfma_f32_16x16x32_bf16 v[140:143], v[220:223], v[88:91], v[140:143]
	v_mfma_f32_16x16x32_bf16 v[152:155], v[220:223], v[96:99], v[152:155]
	ds_read_b128 v[220:223], v174 offset:256
	s_waitcnt lgkmcnt(5)
	v_mfma_f32_16x16x32_bf16 v[144:147], v[224:227], v[88:91], v[144:147]
	v_mfma_f32_16x16x32_bf16 v[160:163], v[224:227], v[96:99], v[160:163]
	ds_read_b128 v[224:227], v174 offset:6656
	s_waitcnt lgkmcnt(5)
	v_mfma_f32_16x16x32_bf16 v[132:135], v[170:173], v[76:79], v[132:135]
	v_mfma_f32_16x16x32_bf16 v[148:151], v[170:173], v[84:87], v[148:151]
	ds_read_b128 v[170:173], v174 offset:13056
	s_waitcnt lgkmcnt(5)
	v_mfma_f32_16x16x32_bf16 v[136:139], v[208:211], v[76:79], v[136:139]
	v_mfma_f32_16x16x32_bf16 v[156:159], v[208:211], v[84:87], v[156:159]
	ds_read_b128 v[208:211], v174 offset:19456
	s_waitcnt lgkmcnt(5)
	v_mfma_f32_16x16x32_bf16 v[140:143], v[212:215], v[76:79], v[140:143]
	v_mfma_f32_16x16x32_bf16 v[152:155], v[212:215], v[84:87], v[152:155]
	ds_read_b128 v[212:215], v174 offset:320
	s_waitcnt lgkmcnt(5)
	v_mfma_f32_16x16x32_bf16 v[144:147], v[216:219], v[76:79], v[144:147]
	v_mfma_f32_16x16x32_bf16 v[160:163], v[216:219], v[84:87], v[160:163]
	ds_read_b128 v[216:219], v174 offset:6720
	s_waitcnt lgkmcnt(5)
	v_mfma_f32_16x16x32_bf16 v[132:135], v[220:223], v[72:75], v[132:135]
	v_mfma_f32_16x16x32_bf16 v[148:151], v[220:223], v[80:83], v[148:151]
	ds_read_b128 v[220:223], v174 offset:13120
	s_waitcnt lgkmcnt(5)
	v_mfma_f32_16x16x32_bf16 v[136:139], v[224:227], v[72:75], v[136:139]
	v_mfma_f32_16x16x32_bf16 v[156:159], v[224:227], v[80:83], v[156:159]
	ds_read_b128 v[224:227], v174 offset:19520
	s_waitcnt lgkmcnt(5)
	v_mfma_f32_16x16x32_bf16 v[140:143], v[170:173], v[72:75], v[140:143]
	v_mfma_f32_16x16x32_bf16 v[152:155], v[170:173], v[80:83], v[152:155]
	s_waitcnt lgkmcnt(4)
	v_mfma_f32_16x16x32_bf16 v[144:147], v[208:211], v[72:75], v[144:147]
	v_mfma_f32_16x16x32_bf16 v[160:163], v[208:211], v[80:83], v[160:163]
	s_waitcnt lgkmcnt(3)
	v_mfma_f32_16x16x32_bf16 v[132:135], v[212:215], v[64:67], v[132:135]
	v_mfma_f32_16x16x32_bf16 v[148:151], v[212:215], v[68:71], v[148:151]
	s_waitcnt lgkmcnt(2)
	v_mfma_f32_16x16x32_bf16 v[136:139], v[216:219], v[64:67], v[136:139]
	v_mfma_f32_16x16x32_bf16 v[156:159], v[216:219], v[68:71], v[156:159]
	s_waitcnt lgkmcnt(1)
	v_mfma_f32_16x16x32_bf16 v[140:143], v[220:223], v[64:67], v[140:143]
	v_mfma_f32_16x16x32_bf16 v[152:155], v[220:223], v[68:71], v[152:155]
	s_waitcnt lgkmcnt(0)
	v_mfma_f32_16x16x32_bf16 v[144:147], v[224:227], v[64:67], v[144:147]
	v_mfma_f32_16x16x32_bf16 v[160:163], v[224:227], v[68:71], v[160:163]
	s_cbranch_scc1 .LBB0_144
; __device__ __forceinline__ void attn_phase(LAS unsigned char* lds, const bf16_t* Q, const bf16_t* KN, const bf16_t* P, const bf16_t* VT, bf16_t* CAT, int bid, int G, const int tid) {
;     ...
;                 if (kt * 64 + 63 > qlo) {
; #pragma unroll
;                     for (int kb = 0; kb < 4; ++kb)
; #pragma unroll
;                         for (int qi = 0; qi < 2; ++qi)
; #pragma unroll
;                             for (int j = 0; j < 4; ++j) { const int key = kt * 64 + kb * 16 + fq * 4 + j, q = qlo + qi * 16 + fr; if (key > q) s[kb][qi][j] = -INFINITY; }
;                 }
	v_add_u32_e32 v171, s30, v242
	v_cmp_gt_i32_e32 vcc, v171, v244
	v_mov_b32_e32 v170, s78
	v_cmp_lt_i32_e64 s[4:5], v171, v244
	v_cndmask_b32_e32 v170, v132, v170, vcc
	v_add_u32_e32 v172, 2, v171
	v_cndmask_b32_e64 v132, v170, v132, s[4:5]
	v_cndmask_b32_e64 v133, v234, v133, s[4:5]
	v_cmp_le_i32_e64 s[4:5], v172, v244
	v_add_u32_e32 v173, 3, v171
	v_mov_b32_e32 v170, s78
	v_cndmask_b32_e64 v134, v234, v134, s[4:5]
	v_cmp_le_i32_e64 s[4:5], v173, v244
	v_add_u32_e32 v174, 19, v171
	v_add_u32_e32 v175, 35, v171
	v_cndmask_b32_e64 v135, v234, v135, s[4:5]
	v_cmp_gt_i32_e64 s[4:5], v171, v199
	s_nop 1
	v_cndmask_b32_e64 v170, v148, v170, s[4:5]
	v_cmp_lt_i32_e64 s[4:5], v171, v199
	s_nop 1
	v_cndmask_b32_e64 v148, v170, v148, s[4:5]
	v_cndmask_b32_e64 v149, v234, v149, s[4:5]
	v_cmp_le_i32_e64 s[4:5], v172, v199
	v_add_u32_e32 v170, 16, v171
	v_add_u32_e32 v172, 17, v171
	v_cndmask_b32_e64 v150, v234, v150, s[4:5]
	v_cmp_le_i32_e64 s[4:5], v173, v199
	v_add_u32_e32 v173, 18, v171
	s_nop 0
	v_cndmask_b32_e64 v151, v234, v151, s[4:5]
	v_cmp_gt_i32_e64 s[4:5], v170, v244
	v_mov_b32_e32 v170, s78
	v_cndmask_b32_e32 v156, v156, v170, vcc
	v_cmp_le_i32_e32 vcc, v172, v199
	v_cndmask_b32_e64 v136, v136, v170, s[4:5]
	v_cmp_le_i32_e64 s[4:5], v172, v244
	v_cndmask_b32_e32 v157, v234, v157, vcc
	v_cmp_le_i32_e32 vcc, v173, v199
	v_add_u32_e32 v172, 32, v171
	v_cndmask_b32_e64 v137, v234, v137, s[4:5]
	v_cndmask_b32_e32 v158, v234, v158, vcc
	v_cmp_le_i32_e32 vcc, v174, v199
	v_cmp_le_i32_e64 s[4:5], v173, v244
	v_add_u32_e32 v173, 33, v171
	v_cndmask_b32_e32 v159, v234, v159, vcc
	v_cmp_gt_i32_e32 vcc, v172, v244
	v_cndmask_b32_e64 v138, v234, v138, s[4:5]
	v_cmp_le_i32_e64 s[4:5], v174, v244
	v_cndmask_b32_e32 v140, v140, v170, vcc
	v_cmp_le_i32_e32 vcc, v173, v244
	v_add_u32_e32 v174, 34, v171
	v_cndmask_b32_e64 v139, v234, v139, s[4:5]
	v_cndmask_b32_e32 v141, v234, v141, vcc
	v_cmp_le_i32_e32 vcc, v174, v244
	s_nop 1
	v_cndmask_b32_e32 v142, v234, v142, vcc
	v_cmp_le_i32_e32 vcc, v175, v244
	s_nop 1
	v_cndmask_b32_e32 v143, v234, v143, vcc
	v_cmp_gt_i32_e32 vcc, v172, v199
	v_add_u32_e32 v172, 48, v171
	s_nop 0
	v_cndmask_b32_e32 v152, v152, v170, vcc
	v_cmp_le_i32_e32 vcc, v173, v199
	v_add_u32_e32 v173, 49, v171
	s_nop 0
	v_cndmask_b32_e32 v153, v234, v153, vcc
	v_cmp_le_i32_e32 vcc, v174, v199
	v_add_u32_e32 v174, 50, v171
	v_add_u32_e32 v171, 51, v171
	v_cndmask_b32_e32 v154, v234, v154, vcc
	v_cmp_le_i32_e32 vcc, v175, v199
	s_nop 1
	v_cndmask_b32_e32 v155, v234, v155, vcc
	v_cmp_gt_i32_e32 vcc, v172, v244
	s_nop 1
	v_cndmask_b32_e32 v144, v144, v170, vcc
	v_cmp_le_i32_e32 vcc, v173, v244
	s_nop 1
	v_cndmask_b32_e32 v145, v234, v145, vcc
	v_cmp_le_i32_e32 vcc, v174, v244
	s_nop 1
	v_cndmask_b32_e32 v146, v234, v146, vcc
	v_cmp_le_i32_e32 vcc, v171, v244
	s_nop 1
	v_cndmask_b32_e32 v147, v234, v147, vcc
	v_cmp_gt_i32_e32 vcc, v172, v199
	s_nop 1
	v_cndmask_b32_e32 v160, v160, v170, vcc
	v_cmp_le_i32_e32 vcc, v173, v199
	s_nop 1
	v_cndmask_b32_e32 v161, v234, v161, vcc
	v_cmp_le_i32_e32 vcc, v174, v199
	s_nop 1
	v_cndmask_b32_e32 v162, v234, v162, vcc
	v_cmp_le_i32_e32 vcc, v171, v199
	s_nop 1
	v_cndmask_b32_e32 v163, v234, v163, vcc
	s_branch .LBB0_144
